# readout0 GEMM: rotate XCD->supertile assignment by 3 so the XCD with 3 readout supertiles has only 10 GEMM1 supertiles in the following barrier-free phase (tile-schedule balance)
# speedup vs baseline: 1.0061x; 1.0015x over previous
.LBB0_531:
	s_cmp_le_i32 s30, s6
	s_cselect_b64 s[0:1], -1, 0
	s_cmp_lt_i32 s6, s31
	s_cselect_b64 s[2:3], -1, 0
	s_and_b64 s[0:1], s[0:1], s[2:3]
	s_andn2_b64 vcc, exec, s[0:1]
	s_cbranch_vccnz .LBB0_115
	v_mov_b32_e32 v2, v228
	v_readlane_b32 s6, v253, 36
	v_readfirstlane_b32 s2, v2
	s_ashr_i32 s1, s2, 6
	s_lshl_b32 s0, s1, 3
	v_bfe_u32 v0, v2, 3, 3
	v_or_b32_e32 v3, s0, v0
	v_readlane_b32 s3, v252, 40
	v_readlane_b32 s8, v252, 39
	s_add_i32 s9, s8, 3
	s_and_b32 s9, s9, 7
	s_sub_i32 s9, s9, s8
	s_lshl_b32 s9, s9, 10
	s_add_i32 s3, s3, s9
	v_readlane_b32 s7, v253, 37
	v_lshrrev_b32_e32 v1, 1, v3
	v_add_u32_e32 v4, s3, v3
	s_load_dword s14, s[6:7], 0x0
	v_xor_b32_e32 v1, v1, v2
	v_ashrrev_i32_e32 v5, 31, v4
	v_readlane_b32 s6, v252, 31
	v_lshlrev_b64 v[4:5], 12, v[4:5]
	v_readlane_b32 s7, v252, 32
	v_lshlrev_b32_e32 v6, 4, v1
	v_and_b32_e32 v176, 0x70, v6
	v_lshl_add_u64 v[4:5], s[6:7], 0, v[4:5]
	v_readlane_b32 s3, v252, 41
	s_lshl_b32 s15, s1, 10
	v_lshl_add_u64 v[4:5], v[4:5], 0, v[176:177]
	v_add_u32_e32 v6, s3, v3
	s_mov_b32 m0, s15
	s_waitcnt vmcnt(0)
	s_waitcnt lgkmcnt(0)
	s_barrier
	v_ashrrev_i32_e32 v7, 31, v6
	v_readlane_b32 s6, v252, 37
	global_load_lds_dwordx4 v[4:5], off
	v_lshl_add_u64 v[8:9], v[4:5], 0, s[94:95]
	s_add_i32 m0, s15, 0x2000
	v_lshlrev_b64 v[6:7], 12, v[6:7]
	v_readlane_b32 s7, v252, 38
	global_load_lds_dwordx4 v[8:9], off
	v_lshl_add_u64 v[8:9], v[4:5], 0, s[36:37]
	s_add_i32 m0, s15, 0x4000
	v_lshl_add_u64 v[6:7], s[6:7], 0, v[6:7]
	global_load_lds_dwordx4 v[8:9], off
	v_lshl_add_u64 v[8:9], v[4:5], 0, s[4:5]
	s_add_i32 m0, s15, 0x6000
	v_lshl_add_u64 v[6:7], v[6:7], 0, v[176:177]
	global_load_lds_dwordx4 v[8:9], off
	s_add_i32 m0, s15, 0x8000
	v_lshl_add_u64 v[8:9], v[6:7], 0, s[94:95]
	global_load_lds_dwordx4 v[6:7], off
	s_add_i32 m0, s15, 0xa000
	s_mov_b64 s[6:7], 0x80
	global_load_lds_dwordx4 v[8:9], off
	v_lshl_add_u64 v[8:9], v[4:5], 0, s[6:7]
	s_add_i32 m0, s15, 0xc000
	s_mov_b64 s[8:9], 0x40080
	v_lshl_add_u64 v[10:11], v[6:7], 0, s[6:7]
	global_load_lds_dwordx4 v[8:9], off
	v_lshl_add_u64 v[8:9], v[4:5], 0, s[8:9]
	s_add_i32 m0, s15, 0xe000
	s_mov_b64 s[6:7], 0x80080
	global_load_lds_dwordx4 v[8:9], off
	v_lshl_add_u64 v[8:9], v[4:5], 0, s[6:7]
	s_add_i32 m0, s15, 0x10000
	s_mov_b64 s[6:7], 0xc0080
	global_load_lds_dwordx4 v[8:9], off
	v_lshl_add_u64 v[4:5], v[4:5], 0, s[6:7]
	s_add_i32 m0, s15, 0x12000
	s_mov_b64 s[82:83], s[76:77]
	global_load_lds_dwordx4 v[4:5], off
	s_add_i32 m0, s15, 0x14000
	v_lshl_add_u64 v[4:5], v[6:7], 0, s[8:9]
	global_load_lds_dwordx4 v[10:11], off
	s_add_i32 m0, s15, 0x16000
	s_cmpk_gt_u32 s2, 0xff
	global_load_lds_dwordx4 v[4:5], off
	s_waitcnt vmcnt(6)
	s_mov_b64 s[78:79], s[66:67]
	s_mov_b64 s[76:77], s[64:65]
	s_mov_b64 s[66:67], s[62:63]
	s_mov_b64 s[64:65], s[60:61]
	s_mov_b64 s[62:63], s[58:59]
	s_mov_b64 s[60:61], s[56:57]
	s_mov_b64 s[58:59], s[34:35]
	s_mov_b64 s[34:35], s[54:55]
	s_cselect_b64 s[38:39], -1, 0
	s_cmpk_lt_u32 s2, 0x100
	s_waitcnt vmcnt(0) lgkmcnt(0)
	s_barrier
	s_cbranch_scc1 .LBB0_534
	s_setprio 1
.LBB0_534:
	v_and_b32_e32 v3, 63, v2
	v_and_b32_e32 v4, 15, v2
	v_lshrrev_b32_e32 v3, 4, v3
	v_lshrrev_b32_e32 v5, 1, v2
	v_bfe_u32 v2, v2, 1, 3
	v_bitop3_b32 v2, v3, v2, 4 bitop3:0x36
	s_and_b32 s1, s1, 1
	v_lshlrev_b32_e32 v6, 7, v4
	v_lshlrev_b32_e32 v155, 4, v2
	v_lshlrev_b32_e32 v2, 2, v3
	s_lshr_b32 s16, s14, 3
	v_lshl_or_b32 v154, s1, 13, v6
	v_lshl_or_b32 v157, s1, 6, v2
	v_and_b32_e32 v1, 7, v1
	v_add_u32_e32 v158, s0, v0
	v_readlane_b32 s0, v252, 58
	s_ashr_i32 s2, s2, 7
	s_add_i32 s3, s16, s25
	v_lshlrev_b32_e32 v176, 4, v1
	v_readlane_b32 s1, v252, 59
	s_cmp_gt_u32 s3, 31
	s_cselect_b32 s18, s25, s3
	v_lshl_add_u64 v[130:131], s[0:1], 0, v[176:177]
	v_readlane_b32 s0, v252, 60
	v_readlane_b32 s3, v252, 39
	v_readlane_b32 s6, v253, 40
	v_readlane_b32 s1, v252, 61
	s_cselect_b32 s17, s6, s3
	v_lshl_or_b32 v152, s2, 13, v6
	v_lshl_or_b32 v156, s2, 6, v4
	v_readlane_b32 s2, v252, 56
	v_lshl_add_u64 v[132:133], s[0:1], 0, v[176:177]
	v_readlane_b32 s0, v252, 62
	v_bitop3_b32 v5, v5, v3, 7 bitop3:0x6c
	v_readlane_b32 s3, v252, 57
	v_readlane_b32 s1, v252, 63
	v_readlane_b32 s92, v252, 35
	s_mov_b64 s[56:57], s[22:23]
	v_lshlrev_b32_e32 v153, 4, v5
	v_lshl_add_u64 v[128:129], s[2:3], 0, v[176:177]
	v_lshl_add_u64 v[134:135], s[0:1], 0, v[176:177]
	s_mov_b32 s11, 0
	s_mov_b32 s21, 0
	s_mov_b32 s20, 0
	v_readlane_b32 s7, v252, 41
	v_readlane_b32 s10, v252, 40
	v_readlane_b32 s93, v252, 36
	v_readlane_b32 s0, v252, 39
	s_add_i32 s1, s0, 3
	s_and_b32 s1, s1, 7
	s_sub_i32 s1, s1, s0
	s_add_i32 s17, s17, s1
	s_lshl_b32 s1, s1, 10
	s_add_i32 s10, s10, s1
	s_branch .LBB0_537
